# last grid barrier (FF2 -> gate) replaced by a row-panel rendezvous of the four tile owners; only the sample-row producers wait for the whole grid; h2 tile and FF2 split-K partials stored write-through
# baseline (speedup 1.0000x reference)
.LBB0_942:
	s_and_b32 s38, s9, -16
	s_nop 1
	v_or_b32_e32 v10, s38, v0
	v_ashrrev_i32_e32 v11, 31, v10
	s_and_b32 s25, s24, 3
	v_lshlrev_b64 v[138:139], 13, v[10:11]
	s_lshl_b32 s34, s25, 11
	v_lshl_add_u64 v[138:139], s[16:17], 0, v[138:139]
	v_lshl_add_u64 v[138:139], v[138:139], 0, s[34:35]
	v_lshl_add_u64 v[134:135], v[4:5], 0, s[34:35]
	v_lshl_add_u64 v[166:167], v[138:139], 0, v[6:7]
	global_load_dwordx4 v[10:13], v[134:135], off
	global_load_dwordx4 v[14:17], v[134:135], off offset:64
	global_load_dwordx4 v[18:21], v[134:135], off offset:128
	global_load_dwordx4 v[22:25], v[134:135], off offset:192
	global_load_dwordx4 v[26:29], v[134:135], off offset:256
	global_load_dwordx4 v[30:33], v[134:135], off offset:320
	global_load_dwordx4 v[34:37], v[134:135], off offset:384
	global_load_dwordx4 v[38:41], v[134:135], off offset:448
	global_load_dwordx4 v[42:45], v[134:135], off offset:512
	global_load_dwordx4 v[46:49], v[134:135], off offset:576
	global_load_dwordx4 v[50:53], v[134:135], off offset:640
	global_load_dwordx4 v[54:57], v[134:135], off offset:704
	global_load_dwordx4 v[58:61], v[134:135], off offset:768
	global_load_dwordx4 v[62:65], v[134:135], off offset:832
	global_load_dwordx4 v[66:69], v[134:135], off offset:896
	global_load_dwordx4 v[70:73], v[134:135], off offset:960
	global_load_dwordx4 v[74:77], v[134:135], off offset:1024
	global_load_dwordx4 v[78:81], v[134:135], off offset:1088
	global_load_dwordx4 v[82:85], v[134:135], off offset:1152
	global_load_dwordx4 v[86:89], v[134:135], off offset:1216
	global_load_dwordx4 v[90:93], v[134:135], off offset:1280
	global_load_dwordx4 v[94:97], v[134:135], off offset:1344
	global_load_dwordx4 v[98:101], v[134:135], off offset:1408
	global_load_dwordx4 v[102:105], v[134:135], off offset:1472
	global_load_dwordx4 v[106:109], v[134:135], off offset:1536
	global_load_dwordx4 v[110:113], v[134:135], off offset:1600
	global_load_dwordx4 v[114:117], v[134:135], off offset:1664
	global_load_dwordx4 v[118:121], v[134:135], off offset:1728
	global_load_dwordx4 v[122:125], v[134:135], off offset:1792
	global_load_dwordx4 v[126:129], v[134:135], off offset:1856
	global_load_dwordx4 v[130:133], v[134:135], off offset:1920
	s_nop 0
	global_load_dwordx4 v[134:137], v[134:135], off offset:1984
	s_nop 0
	global_load_dwordx4 v[138:141], v[166:167], off
	global_load_dwordx4 v[142:145], v[166:167], off offset:64
	global_load_dwordx4 v[146:149], v[166:167], off offset:128
	global_load_dwordx4 v[150:153], v[166:167], off offset:192
	global_load_dwordx4 v[154:157], v[166:167], off offset:256
	global_load_dwordx4 v[158:161], v[166:167], off offset:320
	global_load_dwordx4 v[162:165], v[166:167], off offset:384
	v_lshl_add_u32 v2, s25, 7, v1
	s_ashr_i32 s39, s38, 31
	s_add_i32 s24, s24, s33
	s_add_i32 s9, s9, s14
	s_cmpk_lt_i32 s24, 0x100
	s_waitcnt vmcnt(6)
	v_mfma_f32_16x16x32_bf16 v[10:13], v[10:13], v[138:141], 0
	global_load_dwordx4 v[138:141], v[166:167], off offset:448
	s_waitcnt vmcnt(6)
	v_mfma_f32_16x16x32_bf16 v[10:13], v[14:17], v[142:145], v[10:13]
	global_load_dwordx4 v[14:17], v[166:167], off offset:512
	s_waitcnt vmcnt(6)
	v_mfma_f32_16x16x32_bf16 v[10:13], v[18:21], v[146:149], v[10:13]
	global_load_dwordx4 v[18:21], v[166:167], off offset:576
	s_waitcnt vmcnt(6)
	v_mfma_f32_16x16x32_bf16 v[10:13], v[22:25], v[150:153], v[10:13]
	global_load_dwordx4 v[22:25], v[166:167], off offset:640
	s_waitcnt vmcnt(6)
	v_mfma_f32_16x16x32_bf16 v[10:13], v[26:29], v[154:157], v[10:13]
	global_load_dwordx4 v[26:29], v[166:167], off offset:704
	s_waitcnt vmcnt(6)
	v_mfma_f32_16x16x32_bf16 v[10:13], v[30:33], v[158:161], v[10:13]
	global_load_dwordx4 v[30:33], v[166:167], off offset:768
	s_waitcnt vmcnt(6)
	v_mfma_f32_16x16x32_bf16 v[10:13], v[34:37], v[162:165], v[10:13]
	global_load_dwordx4 v[34:37], v[166:167], off offset:832
	s_waitcnt vmcnt(6)
	v_mfma_f32_16x16x32_bf16 v[10:13], v[38:41], v[138:141], v[10:13]
	global_load_dwordx4 v[38:41], v[166:167], off offset:896
	s_waitcnt vmcnt(6)
	v_mfma_f32_16x16x32_bf16 v[10:13], v[42:45], v[14:17], v[10:13]
	global_load_dwordx4 v[14:17], v[166:167], off offset:960
	s_waitcnt vmcnt(6)
	v_mfma_f32_16x16x32_bf16 v[10:13], v[46:49], v[18:21], v[10:13]
	global_load_dwordx4 v[18:21], v[166:167], off offset:1024
	s_waitcnt vmcnt(6)
	v_mfma_f32_16x16x32_bf16 v[10:13], v[50:53], v[22:25], v[10:13]
	global_load_dwordx4 v[22:25], v[166:167], off offset:1088
	s_waitcnt vmcnt(6)
	v_mfma_f32_16x16x32_bf16 v[10:13], v[54:57], v[26:29], v[10:13]
	global_load_dwordx4 v[26:29], v[166:167], off offset:1152
	s_waitcnt vmcnt(6)
	v_mfma_f32_16x16x32_bf16 v[10:13], v[58:61], v[30:33], v[10:13]
	global_load_dwordx4 v[30:33], v[166:167], off offset:1216
	s_waitcnt vmcnt(6)
	v_mfma_f32_16x16x32_bf16 v[10:13], v[62:65], v[34:37], v[10:13]
	global_load_dwordx4 v[34:37], v[166:167], off offset:1280
	s_waitcnt vmcnt(6)
	v_mfma_f32_16x16x32_bf16 v[10:13], v[66:69], v[38:41], v[10:13]
	global_load_dwordx4 v[38:41], v[166:167], off offset:1344
	s_waitcnt vmcnt(6)
	v_mfma_f32_16x16x32_bf16 v[10:13], v[70:73], v[14:17], v[10:13]
	global_load_dwordx4 v[14:17], v[166:167], off offset:1408
	s_waitcnt vmcnt(6)
	v_mfma_f32_16x16x32_bf16 v[10:13], v[74:77], v[18:21], v[10:13]
	global_load_dwordx4 v[18:21], v[166:167], off offset:1472
	s_waitcnt vmcnt(6)
	v_mfma_f32_16x16x32_bf16 v[10:13], v[78:81], v[22:25], v[10:13]
	global_load_dwordx4 v[22:25], v[166:167], off offset:1536
	s_waitcnt vmcnt(6)
	v_mfma_f32_16x16x32_bf16 v[10:13], v[82:85], v[26:29], v[10:13]
	global_load_dwordx4 v[26:29], v[166:167], off offset:1600
	s_waitcnt vmcnt(6)
	v_mfma_f32_16x16x32_bf16 v[10:13], v[86:89], v[30:33], v[10:13]
	global_load_dwordx4 v[30:33], v[166:167], off offset:1664
	s_waitcnt vmcnt(6)
	v_mfma_f32_16x16x32_bf16 v[10:13], v[90:93], v[34:37], v[10:13]
	global_load_dwordx4 v[34:37], v[166:167], off offset:1728
	s_waitcnt vmcnt(6)
	v_mfma_f32_16x16x32_bf16 v[10:13], v[94:97], v[38:41], v[10:13]
	global_load_dwordx4 v[38:41], v[166:167], off offset:1792
	s_waitcnt vmcnt(6)
	v_mfma_f32_16x16x32_bf16 v[10:13], v[98:101], v[14:17], v[10:13]
	global_load_dwordx4 v[14:17], v[166:167], off offset:1856
	s_waitcnt vmcnt(6)
	v_mfma_f32_16x16x32_bf16 v[10:13], v[102:105], v[18:21], v[10:13]
	global_load_dwordx4 v[18:21], v[166:167], off offset:1920
	s_waitcnt vmcnt(6)
	v_mfma_f32_16x16x32_bf16 v[10:13], v[106:109], v[22:25], v[10:13]
	global_load_dwordx4 v[22:25], v[166:167], off offset:1984
	s_waitcnt vmcnt(6)
	v_mfma_f32_16x16x32_bf16 v[10:13], v[110:113], v[26:29], v[10:13]
	v_lshlrev_b64 v[26:27], 12, v[2:3]
	v_lshl_add_u64 v[26:27], s[12:13], 0, v[26:27]
	v_lshl_add_u64 v[26:27], s[38:39], 2, v[26:27]
	s_waitcnt vmcnt(5)
	v_mfma_f32_16x16x32_bf16 v[10:13], v[114:117], v[30:33], v[10:13]
	v_lshl_add_u64 v[26:27], v[26:27], 0, v[8:9]
	v_add_co_u32_e32 v28, vcc, s15, v26
	s_waitcnt vmcnt(4)
	v_mfma_f32_16x16x32_bf16 v[10:13], v[118:121], v[34:37], v[10:13]
	v_addc_co_u32_e32 v29, vcc, 0, v27, vcc
	v_add_co_u32_e32 v30, vcc, 0x2000, v26
	s_waitcnt vmcnt(3)
	v_mfma_f32_16x16x32_bf16 v[10:13], v[122:125], v[38:41], v[10:13]
	v_addc_co_u32_e32 v31, vcc, 0, v27, vcc
	s_waitcnt vmcnt(2)
	v_mfma_f32_16x16x32_bf16 v[10:13], v[126:129], v[14:17], v[10:13]
	v_add_co_u32_e32 v14, vcc, 0x3000, v26
	s_waitcnt vmcnt(1)
	v_mfma_f32_16x16x32_bf16 v[10:13], v[130:133], v[18:21], v[10:13]
	v_addc_co_u32_e32 v15, vcc, 0, v27, vcc
	s_waitcnt vmcnt(0)
	v_mfma_f32_16x16x32_bf16 v[10:13], v[134:137], v[22:25], v[10:13]
	s_nop 7
	global_store_dword v[26:27], v10, off sc1
	global_store_dword v[28:29], v11, off sc1
	global_store_dword v[30:31], v12, off sc1
	global_store_dword v[14:15], v13, off sc1
	s_cbranch_scc1 .LBB0_942

.LBB0_1004:
	s_and_b32 s10, s12, -16
	s_nop 1
	v_or_b32_e32 v10, s10, v0
	v_ashrrev_i32_e32 v11, 31, v10
	s_and_b32 s11, s15, 3
	v_lshlrev_b64 v[138:139], 13, v[10:11]
	s_lshl_b32 s8, s11, 11
	v_lshl_add_u64 v[138:139], s[16:17], 0, v[138:139]
	v_lshl_add_u64 v[138:139], v[138:139], 0, s[8:9]
	v_lshl_add_u64 v[134:135], v[4:5], 0, s[8:9]
	v_lshl_add_u64 v[166:167], v[138:139], 0, v[6:7]
	global_load_dwordx4 v[10:13], v[134:135], off
	global_load_dwordx4 v[14:17], v[134:135], off offset:64
	global_load_dwordx4 v[18:21], v[134:135], off offset:128
	global_load_dwordx4 v[22:25], v[134:135], off offset:192
	global_load_dwordx4 v[26:29], v[134:135], off offset:256
	global_load_dwordx4 v[30:33], v[134:135], off offset:320
	global_load_dwordx4 v[34:37], v[134:135], off offset:384
	global_load_dwordx4 v[38:41], v[134:135], off offset:448
	global_load_dwordx4 v[42:45], v[134:135], off offset:512
	global_load_dwordx4 v[46:49], v[134:135], off offset:576
	global_load_dwordx4 v[50:53], v[134:135], off offset:640
	global_load_dwordx4 v[54:57], v[134:135], off offset:704
	global_load_dwordx4 v[58:61], v[134:135], off offset:768
	global_load_dwordx4 v[62:65], v[134:135], off offset:832
	global_load_dwordx4 v[66:69], v[134:135], off offset:896
	global_load_dwordx4 v[70:73], v[134:135], off offset:960
	global_load_dwordx4 v[74:77], v[134:135], off offset:1024
	global_load_dwordx4 v[78:81], v[134:135], off offset:1088
	global_load_dwordx4 v[82:85], v[134:135], off offset:1152
	global_load_dwordx4 v[86:89], v[134:135], off offset:1216
	global_load_dwordx4 v[90:93], v[134:135], off offset:1280
	global_load_dwordx4 v[94:97], v[134:135], off offset:1344
	global_load_dwordx4 v[98:101], v[134:135], off offset:1408
	global_load_dwordx4 v[102:105], v[134:135], off offset:1472
	global_load_dwordx4 v[106:109], v[134:135], off offset:1536
	global_load_dwordx4 v[110:113], v[134:135], off offset:1600
	global_load_dwordx4 v[114:117], v[134:135], off offset:1664
	global_load_dwordx4 v[118:121], v[134:135], off offset:1728
	global_load_dwordx4 v[122:125], v[134:135], off offset:1792
	global_load_dwordx4 v[126:129], v[134:135], off offset:1856
	global_load_dwordx4 v[130:133], v[134:135], off offset:1920
	s_nop 0
	global_load_dwordx4 v[134:137], v[134:135], off offset:1984
	s_nop 0
	global_load_dwordx4 v[138:141], v[166:167], off
	global_load_dwordx4 v[142:145], v[166:167], off offset:64
	global_load_dwordx4 v[146:149], v[166:167], off offset:128
	global_load_dwordx4 v[150:153], v[166:167], off offset:192
	global_load_dwordx4 v[154:157], v[166:167], off offset:256
	global_load_dwordx4 v[158:161], v[166:167], off offset:320
	global_load_dwordx4 v[162:165], v[166:167], off offset:384
	v_lshl_add_u32 v2, s11, 7, v1
	s_ashr_i32 s11, s10, 31
	s_add_i32 s15, s15, s33
	s_add_i32 s12, s12, s13
	s_cmpk_lt_i32 s15, 0x100
	s_waitcnt vmcnt(6)
	v_mfma_f32_16x16x32_bf16 v[10:13], v[10:13], v[138:141], 0
	global_load_dwordx4 v[138:141], v[166:167], off offset:448
	s_waitcnt vmcnt(6)
	v_mfma_f32_16x16x32_bf16 v[10:13], v[14:17], v[142:145], v[10:13]
	global_load_dwordx4 v[14:17], v[166:167], off offset:512
	s_waitcnt vmcnt(6)
	v_mfma_f32_16x16x32_bf16 v[10:13], v[18:21], v[146:149], v[10:13]
	global_load_dwordx4 v[18:21], v[166:167], off offset:576
	s_waitcnt vmcnt(6)
	v_mfma_f32_16x16x32_bf16 v[10:13], v[22:25], v[150:153], v[10:13]
	global_load_dwordx4 v[22:25], v[166:167], off offset:640
	s_waitcnt vmcnt(6)
	v_mfma_f32_16x16x32_bf16 v[10:13], v[26:29], v[154:157], v[10:13]
	global_load_dwordx4 v[26:29], v[166:167], off offset:704
	s_waitcnt vmcnt(6)
	v_mfma_f32_16x16x32_bf16 v[10:13], v[30:33], v[158:161], v[10:13]
	global_load_dwordx4 v[30:33], v[166:167], off offset:768
	s_waitcnt vmcnt(6)
	v_mfma_f32_16x16x32_bf16 v[10:13], v[34:37], v[162:165], v[10:13]
	global_load_dwordx4 v[34:37], v[166:167], off offset:832
	s_waitcnt vmcnt(6)
	v_mfma_f32_16x16x32_bf16 v[10:13], v[38:41], v[138:141], v[10:13]
	global_load_dwordx4 v[38:41], v[166:167], off offset:896
	s_waitcnt vmcnt(6)
	v_mfma_f32_16x16x32_bf16 v[10:13], v[42:45], v[14:17], v[10:13]
	global_load_dwordx4 v[14:17], v[166:167], off offset:960
	s_waitcnt vmcnt(6)
	v_mfma_f32_16x16x32_bf16 v[10:13], v[46:49], v[18:21], v[10:13]
	global_load_dwordx4 v[18:21], v[166:167], off offset:1024
	s_waitcnt vmcnt(6)
	v_mfma_f32_16x16x32_bf16 v[10:13], v[50:53], v[22:25], v[10:13]
	global_load_dwordx4 v[22:25], v[166:167], off offset:1088
	s_waitcnt vmcnt(6)
	v_mfma_f32_16x16x32_bf16 v[10:13], v[54:57], v[26:29], v[10:13]
	global_load_dwordx4 v[26:29], v[166:167], off offset:1152
	s_waitcnt vmcnt(6)
	v_mfma_f32_16x16x32_bf16 v[10:13], v[58:61], v[30:33], v[10:13]
	global_load_dwordx4 v[30:33], v[166:167], off offset:1216
	s_waitcnt vmcnt(6)
	v_mfma_f32_16x16x32_bf16 v[10:13], v[62:65], v[34:37], v[10:13]
	global_load_dwordx4 v[34:37], v[166:167], off offset:1280
	s_waitcnt vmcnt(6)
	v_mfma_f32_16x16x32_bf16 v[10:13], v[66:69], v[38:41], v[10:13]
	global_load_dwordx4 v[38:41], v[166:167], off offset:1344
	s_waitcnt vmcnt(6)
	v_mfma_f32_16x16x32_bf16 v[10:13], v[70:73], v[14:17], v[10:13]
	global_load_dwordx4 v[14:17], v[166:167], off offset:1408
	s_waitcnt vmcnt(6)
	v_mfma_f32_16x16x32_bf16 v[10:13], v[74:77], v[18:21], v[10:13]
	global_load_dwordx4 v[18:21], v[166:167], off offset:1472
	s_waitcnt vmcnt(6)
	v_mfma_f32_16x16x32_bf16 v[10:13], v[78:81], v[22:25], v[10:13]
	global_load_dwordx4 v[22:25], v[166:167], off offset:1536
	s_waitcnt vmcnt(6)
	v_mfma_f32_16x16x32_bf16 v[10:13], v[82:85], v[26:29], v[10:13]
	global_load_dwordx4 v[26:29], v[166:167], off offset:1600
	s_waitcnt vmcnt(6)
	v_mfma_f32_16x16x32_bf16 v[10:13], v[86:89], v[30:33], v[10:13]
	global_load_dwordx4 v[30:33], v[166:167], off offset:1664
	s_waitcnt vmcnt(6)
	v_mfma_f32_16x16x32_bf16 v[10:13], v[90:93], v[34:37], v[10:13]
	global_load_dwordx4 v[34:37], v[166:167], off offset:1728
	s_waitcnt vmcnt(6)
	v_mfma_f32_16x16x32_bf16 v[10:13], v[94:97], v[38:41], v[10:13]
	global_load_dwordx4 v[38:41], v[166:167], off offset:1792
	s_waitcnt vmcnt(6)
	v_mfma_f32_16x16x32_bf16 v[10:13], v[98:101], v[14:17], v[10:13]
	global_load_dwordx4 v[14:17], v[166:167], off offset:1856
	s_waitcnt vmcnt(6)
	v_mfma_f32_16x16x32_bf16 v[10:13], v[102:105], v[18:21], v[10:13]
	global_load_dwordx4 v[18:21], v[166:167], off offset:1920
	s_waitcnt vmcnt(6)
	v_mfma_f32_16x16x32_bf16 v[10:13], v[106:109], v[22:25], v[10:13]
	global_load_dwordx4 v[22:25], v[166:167], off offset:1984
	s_waitcnt vmcnt(6)
	v_mfma_f32_16x16x32_bf16 v[10:13], v[110:113], v[26:29], v[10:13]
	v_lshlrev_b64 v[26:27], 12, v[2:3]
	v_lshl_add_u64 v[26:27], s[4:5], 0, v[26:27]
	v_lshl_add_u64 v[26:27], s[10:11], 2, v[26:27]
	s_waitcnt vmcnt(5)
	v_mfma_f32_16x16x32_bf16 v[10:13], v[114:117], v[30:33], v[10:13]
	v_lshl_add_u64 v[26:27], v[26:27], 0, v[8:9]
	v_add_co_u32_e32 v28, vcc, s14, v26
	s_waitcnt vmcnt(4)
	v_mfma_f32_16x16x32_bf16 v[10:13], v[118:121], v[34:37], v[10:13]
	v_addc_co_u32_e32 v29, vcc, 0, v27, vcc
	v_add_co_u32_e32 v30, vcc, 0x2000, v26
	s_waitcnt vmcnt(3)
	v_mfma_f32_16x16x32_bf16 v[10:13], v[122:125], v[38:41], v[10:13]
	v_addc_co_u32_e32 v31, vcc, 0, v27, vcc
	s_waitcnt vmcnt(2)
	v_mfma_f32_16x16x32_bf16 v[10:13], v[126:129], v[14:17], v[10:13]
	v_add_co_u32_e32 v14, vcc, 0x3000, v26
	s_waitcnt vmcnt(1)
	v_mfma_f32_16x16x32_bf16 v[10:13], v[130:133], v[18:21], v[10:13]
	v_addc_co_u32_e32 v15, vcc, 0, v27, vcc
	s_waitcnt vmcnt(0)
	v_mfma_f32_16x16x32_bf16 v[10:13], v[134:137], v[22:25], v[10:13]
	s_nop 7
	global_store_dword v[26:27], v10, off sc1
	global_store_dword v[28:29], v11, off sc1
	global_store_dword v[30:31], v12, off sc1
	global_store_dword v[14:15], v13, off sc1
	s_cbranch_scc1 .LBB0_1004
.LBB0_1005:
	s_waitcnt vmcnt(0)
	v_readlane_b32 s4, v248, 5
	v_readlane_b32 s5, v248, 6
	s_and_b64 vcc, exec, s[4:5]
	s_barrier
	s_cbranch_vccz .LBB0_1059
	v_mbcnt_lo_u32_b32 v0, -1, 0
	v_mbcnt_hi_u32_b32 v0, -1, v0
	s_nop 0
	v_cmp_eq_u32_e32 vcc, 0, v0
	s_and_saveexec_b64 s[4:5], vcc
	s_cbranch_execz .LBB0_1058
	buffer_wbl2 sc1
	s_cmp_lg_u64 s[36:37], 0
	s_cselect_b32 s10, s79, s78
	v_readlane_b32 s11, v248, 7
	s_add_i32 s10, s10, s11
	s_lshr_b32 s11, s10, 5
	s_lshl_b32 s11, s11, 3
	s_and_b32 s12, s10, 7
	s_add_i32 s11, s11, s12
	s_lshl_b32 s11, s11, 8
	s_add_u32 s8, s0, 0x29000
	s_addc_u32 s9, s1, 0
	s_add_u32 s8, s8, s11
	s_addc_u32 s9, s9, 0
	s_add_u32 s12, s0, 0x28400
	s_addc_u32 s13, s1, 0
	v_mov_b32_e32 v0, 0
	v_mov_b32_e32 v1, 1
	s_waitcnt vmcnt(0) lgkmcnt(0)
	global_atomic_add v0, v1, s[8:9]
	global_atomic_add v0, v1, s[12:13]
	s_mov_b32 s14, 0
.Lp9_wait_panel:
	global_load_dword v2, v0, s[8:9] sc1
	s_waitcnt vmcnt(0)
	v_readfirstlane_b32 s15, v2
	s_cmp_ge_u32 s15, 4
	s_cbranch_scc1 .Lp9_panel_ok
	s_sleep 1
	s_add_i32 s14, s14, 1
	s_cmp_lt_u32 s14, 0x40001
	s_cbranch_scc1 .Lp9_wait_panel
.Lp9_panel_ok:
	s_and_b32 s15, s92, 15
	s_cmp_eq_u32 s15, 2
	s_cbranch_scc0 .Lp9_acq
	s_mov_b32 s14, 0
.Lp9_wait_all:
	global_load_dword v2, v0, s[12:13] sc1
	s_waitcnt vmcnt(0)
	v_readfirstlane_b32 s15, v2
	s_cmp_ge_u32 s15, s33
	s_cbranch_scc1 .Lp9_acq
	s_sleep 1
	s_add_i32 s14, s14, 1
	s_cmp_lt_u32 s14, 0x40001
	s_cbranch_scc1 .Lp9_wait_all
.Lp9_acq:
	buffer_inv sc1
	s_waitcnt vmcnt(0)
